# mix2: one static s_setprio 1 for waves 0-3 for the whole phase, per-section priority flips in the chunk loop deleted
# baseline (speedup 1.0000x reference)
; #define LAS __attribute__((address_space(3)))
; __device__ void phase_mix2(const Params& P, LAS unsigned char* lds, const int G, const int bid) {
;     unsigned char* dob = (unsigned char*)P.out; const float* tot = (const float*)(dob + DO_TOT); const float* tots = (const float*)(dob + DO_TOTS);
;     for (int it = bid; it < 256; it += G) {
;         const int sg = it >> 3, hd = it & 7;
;         const int seqlen = sg < 16 ? 8192 : 2048; const int s = sg < 16 ? (sg & 7) : ((sg - 16) & 1), nseg = sg < 16 ? 8 : 2; const int sg0 = sg - s;
;         for (int pass = 0; pass < 2; ++pass) { const int dir = pass ? 0 : 1;
.LBB0_69:
	s_and_b64 vcc, exec, s[2:3]
	s_cbranch_vccz .LBB0_371
	v_readlane_b32 s0, v255, 19
	s_cmpk_gt_i32 s0, 0xff
	s_cbranch_scc1 .LBB0_371
	v_readfirstlane_b32 s0, v162
	s_nop 3
	s_lshr_b32 s0, s0, 6
	s_cmp_ge_u32 s0, 4
	s_cbranch_scc1 .Lmix_prio_done
	s_setprio 1
